# v023 + prologue hidden-state init with the 4 row pieces loaded together
# baseline (speedup 1.0000x reference)
; #define GAS __attribute__((address_space(1)))
; __device__ __forceinline__ unsigned pk2(float lo, float hi) { f32x2v v = {lo, hi}; bf16x2v b = __builtin_convertvector(v, bf16x2v); return __builtin_bit_cast(unsigned, b); }
; #define GAS __attribute__((address_space(1)))
; DI float wave_sum(float v) { v += swz_xor<1>(v); v += swz_xor<2>(v); v += swz_xor<4>(v); v += swz_xor<8>(v); v += swz_xor<16>(v); return half_sum(v); }
; DI void phase_prologue(KParams P, float* sl) {
;     ...
;       for (int row = gw; row < M; row += nw) {
;           const int b = row / TT, t = row % TT;
;           GAS const f32x4* src = (GAS const f32x4*)((t < 16) ? P->in[1] + (size_t)t * 1024 : P->in[0] + ((size_t)b * SEQ + (t - 16)) * 1024);
;           GAS u32x2* bp = (GAS u32x2*)(HB + (size_t)row * 1024); float sq = 0.f;
; #pragma unroll
;           for (int i = 0; i < 4; ++i) { const f32x4 v = src[lane + 64 * i]; u32x2 w; w.x = pk2(v[0], v[1]); w.y = pk2(v[2], v[3]); bp[lane + 64 * i] = w;
;               sq += (v[0] * v[0] + v[1] * v[1]) + (v[2] * v[2] + v[3] * v[3]); }
;           sq = wave_sum(sq); if (lane < 16) ss0[(size_t)row * 16 + lane] = (lane == 0) ? sq : 0.f;
.LBB0_705:
	s_or_b64 exec, exec, s[8:9]
	v_lshlrev_b64 v[8:9], 12, v[8:9]
	v_lshl_add_u64 v[8:9], v[10:11], 0, v[8:9]
	v_lshl_add_u64 v[20:21], v[8:9], 0, v[64:65]
	global_load_dwordx4 v[8:11], v[20:21], off
	global_load_dwordx4 v[12:15], v[20:21], off offset:1024
	global_load_dwordx4 v[16:19], v[20:21], off offset:2048
	global_load_dwordx4 v[20:23], v[20:21], off offset:3072
	v_ashrrev_i32_e32 v3, 31, v2
	v_lshlrev_b64 v[26:27], 11, v[2:3]
	v_lshl_add_u64 v[24:25], v[6:7], 0, v[26:27]
	s_waitcnt vmcnt(3)
	v_cvt_pk_bf16_f32 v26, v8, v9
	v_cvt_pk_bf16_f32 v27, v10, v11
	global_store_dwordx2 v[24:25], v[26:27], off
	v_mul_f32_e32 v9, v9, v9
	v_mul_f32_e32 v11, v11, v11
	v_fmac_f32_e32 v9, v8, v8
	v_fmac_f32_e32 v11, v10, v10
	v_add_f32_e32 v8, v9, v11
	s_waitcnt vmcnt(3)
	v_cvt_pk_bf16_f32 v28, v12, v13
	v_cvt_pk_bf16_f32 v29, v14, v15
	global_store_dwordx2 v[24:25], v[28:29], off offset:512
	v_mul_f32_e32 v9, v13, v13
	v_mul_f32_e32 v10, v15, v15
	v_fmac_f32_e32 v9, v12, v12
	v_fmac_f32_e32 v10, v14, v14
	v_add_f32_e32 v9, v9, v10
	v_add_f32_e32 v8, v8, v9
	s_waitcnt vmcnt(3)
	v_cvt_pk_bf16_f32 v30, v16, v17
	v_cvt_pk_bf16_f32 v31, v18, v19
	global_store_dwordx2 v[24:25], v[30:31], off offset:1024
	v_mul_f32_e32 v9, v17, v17
	v_mul_f32_e32 v10, v19, v19
	v_fmac_f32_e32 v9, v16, v16
	v_fmac_f32_e32 v10, v18, v18
	v_add_f32_e32 v9, v9, v10
	v_add_f32_e32 v8, v8, v9
	s_waitcnt vmcnt(3)
	v_mul_f32_e32 v9, v21, v21
	v_mul_f32_e32 v10, v23, v23
	v_fmac_f32_e32 v9, v20, v20
	v_fmac_f32_e32 v10, v22, v22
	v_add_f32_e32 v9, v9, v10
	v_add_f32_e32 v8, v8, v9
	ds_swizzle_b32 v9, v8 offset:swizzle(SWAP,1)
	s_waitcnt lgkmcnt(0)
	v_add_f32_e32 v8, v8, v9
	ds_swizzle_b32 v9, v8 offset:swizzle(SWAP,2)
	s_waitcnt lgkmcnt(0)
	v_add_f32_e32 v8, v8, v9
	ds_swizzle_b32 v9, v8 offset:swizzle(SWAP,4)
	s_waitcnt lgkmcnt(0)
	v_add_f32_e32 v8, v8, v9
	ds_swizzle_b32 v9, v8 offset:swizzle(SWAP,8)
	s_waitcnt lgkmcnt(0)
	v_add_f32_e32 v10, v8, v9
	ds_swizzle_b32 v11, v10 offset:swizzle(SWAP,16)
	v_cvt_pk_bf16_f32 v8, v20, v21
	v_cvt_pk_bf16_f32 v9, v22, v23
	global_store_dwordx2 v[24:25], v[8:9], off offset:1536
	s_waitcnt lgkmcnt(0)
	v_add_f32_e32 v8, v10, v11
	v_mov_b32_e32 v9, v8
	s_nop 1
	v_permlane32_swap_b32_e32 v8, v9
	s_and_saveexec_b64 s[8:9], vcc
	s_cbranch_execz .LBB0_700
	v_add_f32_e32 v8, v8, v9
	v_cndmask_b32_e64 v10, 0, v8, s[6:7]
	v_lshlrev_b64 v[8:9], 6, v[2:3]
	v_lshl_add_u64 v[8:9], v[4:5], 0, v[8:9]
	global_store_dword v[8:9], v10, off
	s_branch .LBB0_700
